# phase-0 grid sync replaced by the XCD barrier; gate-up GEMM first K iteration peeled with C=0 (no accumulator zeroing)
# speedup vs baseline: 1.0204x; 1.0204x over previous
; __device__ __forceinline__ unsigned xb_ld(unsigned* p)              { return __hip_atomic_load(p, __ATOMIC_RELAXED, __HIP_MEMORY_SCOPE_AGENT); }
; __device__ __forceinline__ unsigned xb_add(unsigned* p, unsigned v) { return __hip_atomic_fetch_add(p, v, __ATOMIC_RELAXED, __HIP_MEMORY_SCOPE_AGENT); }
; __device__ __forceinline__ void xcd_barrier_complete(unsigned* bar, unsigned x, unsigned& nloc, unsigned& nx) {
;     const unsigned G = gridDim.x * gridDim.y * gridDim.z;
;     unsigned sum, cnt, mine, sp = 0u;
;     for (;;) {
;         sum = 0u; cnt = 0u; mine = 0u;
; #pragma unroll
;         for (unsigned j = 0; j < 16; ++j) { const unsigned c = xb_ld(&bar[XB_XCNT(j)]); sum += c; cnt += (c > 0u) ? 1u : 0u; mine = (j == x) ? c : mine; }
;         if (sum == G) break;
;         __builtin_amdgcn_s_sleep(1);
;         if ((++sp & 255u) == 0u) { if (xb_ld(&bar[XB_TMO])) break; if (sp > XB_SPIN_CAP) { atomicAdd(&bar[XB_TMO], 1u); break; } }
;     }
;     nloc = mine > 0u ? mine : 1u; nx = cnt > 0u ? cnt : 1u;
; }
; __device__ __forceinline__ void xcd_barrier(const XcdBarrier& b) {
;     asm volatile("s_waitcnt vmcnt(0)" ::: "memory");
;     __syncthreads();
;     if (threadIdx.x == 0) {
;         unsigned* bar = b.bar;
;         __builtin_amdgcn_s_waitcnt(0);
;         unsigned nloc = b.st[0], nx = b.st[1];
;         if (nloc == 0u) { xcd_barrier_complete(bar, b.x, nloc, nx); b.st[0] = nloc; b.st[1] = nx; }
;         const unsigned old = xb_add(&bar[XB_XSUB(b.x)], 1u);
;         const unsigned gen = old / nloc;
;         if (old + 1u == (gen + 1u) * nloc) {
;             __builtin_amdgcn_fence(__ATOMIC_RELEASE, "agent");
;             asm volatile("s_waitcnt vmcnt(0)" ::: "memory");
;             const unsigned og = xb_add(&bar[XB_TOP], 1u);
;             const unsigned tg = og / nx;
;             if (og + 1u == (tg + 1u) * nx) xb_add(&bar[XB_TOPGEN], 1u);
;             else XB_SPIN(xb_ld(&bar[XB_TOPGEN]) == tg, bar);
;             __builtin_amdgcn_fence(__ATOMIC_ACQUIRE, "agent");
;             xb_add(&bar[XB_XGEN(b.x)], 1u);
; __global__ void __launch_bounds__(NWAVES * 64, 2) mk_fwd(Args args) {
;     ...
;         if (did && (p + 1 < args.ph_hi || again)) {
;             if (p == 0 && !again) { __syncthreads(); cg::this_grid().sync(); } else xcd_barrier(bar);
.LBB0_14:
	v_readlane_b32 s6, v254, 0
	v_readlane_b32 s7, v254, 1
	s_add_u32 s6, s6, 0xa8
	s_addc_u32 s7, s7, 0
	v_writelane_b32 v254, s6, 3
	s_lshl_b32 s3, s88, 3
	s_cmpk_lt_i32 s88, 0x80
	v_writelane_b32 v254, s7, 4
	v_writelane_b32 v254, s3, 5
	s_cselect_b64 s[6:7], -1, 0
	v_writelane_b32 v254, s6, 6
	v_lshrrev_b32_e32 v1, 20, v0
	v_lshrrev_b32_e32 v0, 10, v0
	v_writelane_b32 v254, s7, 7
	s_add_u32 s6, s0, 0x4200
	s_addc_u32 s7, s1, 0
	v_writelane_b32 v254, s6, 8
	v_or_b32_e32 v0, v0, v1
	v_mbcnt_lo_u32_b32 v1, -1, 0
	v_writelane_b32 v254, s7, 9
	s_add_u32 s6, s0, 0x4400
	s_addc_u32 s7, s1, 0
	v_writelane_b32 v254, s6, 10
	s_mov_b32 s38, 0xfffe0000
	s_mov_b32 s20, 0xfffc0000
	v_writelane_b32 v254, s7, 11
	s_add_u32 s6, s0, 0x4500
	s_addc_u32 s7, s1, 0
	v_writelane_b32 v254, s6, 12
	v_mov_b32_e32 v3, 0
	v_mov_b32_e32 v213, 0x358637bd
	v_writelane_b32 v254, s7, 13
	s_add_u32 s6, s0, 0x4600
	s_addc_u32 s7, s1, 0
	v_writelane_b32 v254, s6, 14
	v_mov_b32_e32 v214, 0x260
	v_mov_b32_e32 v215, 0x3eaaaaab
	v_writelane_b32 v254, s7, 15
	s_add_u32 s6, s0, 0x4700
	s_addc_u32 s7, s1, 0
	v_writelane_b32 v254, s6, 16
	v_mov_b32_e32 v216, 1
	v_mov_b32_e32 v217, 0xff800000
	v_writelane_b32 v254, s7, 17
	s_add_u32 s6, s0, 0x4800
	s_addc_u32 s7, s1, 0
	v_writelane_b32 v254, s6, 18
	v_mov_b32_e32 v218, 0x100
	v_mbcnt_hi_u32_b32 v219, -1, v1
	v_writelane_b32 v254, s7, 19
	s_add_u32 s6, s0, 0x4900
	s_addc_u32 s7, s1, 0
	v_writelane_b32 v254, s6, 20
	v_mov_b32_e32 v224, 0x3f80
	v_mov_b32_e32 v222, 0x3f803f80
	v_writelane_b32 v254, s7, 21
	s_add_u32 s6, s0, 0x4a00
	s_addc_u32 s7, s1, 0
	v_writelane_b32 v254, s6, 22
	v_mov_b32_e32 v223, 1.0
	v_mov_b64_e32 v[196:197], 0x600
	v_writelane_b32 v254, s7, 23
	s_add_u32 s6, s0, 0x4b00
	s_addc_u32 s7, s1, 0
	v_writelane_b32 v254, s6, 24
	v_mov_b64_e32 v[198:199], 0x5ff
	v_mov_b32_e32 v225, 0x19700000
	v_writelane_b32 v254, s7, 25
	s_add_u32 s6, s0, 0x4c00
	s_addc_u32 s7, s1, 0
	v_writelane_b32 v254, s6, 26
	v_mov_b32_e32 v226, 0x19300000
	v_mov_b64_e32 v[200:201], 0x200
	v_writelane_b32 v254, s7, 27
	s_add_u32 s6, s0, 0x4d00
	s_addc_u32 s7, s1, 0
	v_writelane_b32 v254, s6, 28
	v_mov_b64_e32 v[202:203], 0x1ff
	v_mov_b64_e32 v[204:205], 0x1000
	v_writelane_b32 v254, s7, 29
	s_add_u32 s6, s0, 0x4e00
	s_addc_u32 s7, s1, 0
	v_writelane_b32 v254, s6, 30
	v_mov_b64_e32 v[206:207], 0xfff
	s_mov_b32 s68, 0x7600000
	v_writelane_b32 v254, s7, 31
	s_add_u32 s6, s0, 0x4f00
	s_addc_u32 s7, s1, 0
	v_writelane_b32 v254, s6, 32
	s_mov_b32 s35, 0xffff0000
	s_movk_i32 s23, 0x200
	v_writelane_b32 v254, s7, 33
	s_add_u32 s6, s0, 0x5000
	s_addc_u32 s7, s1, 0
	v_writelane_b32 v254, s6, 34
	s_movk_i32 s10, 0xfd80
	s_movk_i32 s11, 0x4000
	v_writelane_b32 v254, s7, 35
	s_add_u32 s6, s0, 0x5100
	s_addc_u32 s7, s1, 0
	v_writelane_b32 v254, s6, 36
	s_movk_i32 s12, 0xa10
	s_mov_b32 s15, 0xf149f2ca
	v_writelane_b32 v254, s7, 37
	s_add_u32 s6, s0, 0x5200
	s_addc_u32 s7, s1, 0
	v_writelane_b32 v254, s6, 38
	s_mov_b32 s17, 0x41000000
	s_movk_i32 s18, 0x1cf
	v_writelane_b32 v254, s7, 39
	s_add_u32 s6, s0, 0x5300
	s_addc_u32 s7, s1, 0
	v_writelane_b32 v254, s6, 40
	s_cmp_eq_u32 s2, 15
	s_movk_i32 s74, 0x7fff
	v_writelane_b32 v254, s7, 41
	s_cselect_b64 s[6:7], -1, 0
	v_writelane_b32 v254, s6, 42
	s_cmp_eq_u32 s2, 14
	s_movk_i32 s69, 0x410
	v_writelane_b32 v254, s7, 43
	s_cselect_b64 s[6:7], -1, 0
	v_writelane_b32 v254, s6, 44
	s_cmp_eq_u32 s2, 13
	s_movk_i32 s89, 0x3cf
	v_writelane_b32 v254, s7, 45
	s_cselect_b64 s[6:7], -1, 0
	v_writelane_b32 v254, s6, 46
	s_cmp_eq_u32 s2, 12
	s_mov_b32 s97, 0xbfb8aa3b
	v_writelane_b32 v254, s7, 47
	s_cselect_b64 s[6:7], -1, 0
	v_writelane_b32 v254, s6, 48
	s_cmp_eq_u32 s2, 11
	s_mov_b32 s75, 0x3cf5c28f
	v_writelane_b32 v254, s7, 49
	s_cselect_b64 s[6:7], -1, 0
	v_writelane_b32 v254, s6, 50
	s_cmp_eq_u32 s2, 10
	s_mov_b32 s29, 0
	v_writelane_b32 v254, s7, 51
	s_cselect_b64 s[6:7], -1, 0
	v_writelane_b32 v254, s6, 52
	s_cmp_eq_u32 s2, 9
	s_mov_b64 s[30:31], 0x20000
	v_writelane_b32 v254, s7, 53
	s_cselect_b64 s[6:7], -1, 0
	v_writelane_b32 v254, s6, 54
	s_cmp_eq_u32 s2, 8
	s_mov_b32 s34, 0x3fb8aa3b
	v_writelane_b32 v254, s7, 55
	s_cselect_b64 s[6:7], -1, 0
	v_writelane_b32 v254, s6, 56
	s_cmp_eq_u32 s2, 7
	s_mov_b64 s[80:81], 0x40000
	v_writelane_b32 v254, s7, 57
	s_cselect_b64 s[6:7], -1, 0
	v_writelane_b32 v254, s6, 58
	s_cmp_eq_u32 s2, 6
	s_mov_b64 s[24:25], 0x60000
	v_writelane_b32 v254, s7, 59
	s_cselect_b64 s[6:7], -1, 0
	v_writelane_b32 v254, s6, 60
	s_cmp_eq_u32 s2, 5
	s_mov_b32 s39, -1
	v_writelane_b32 v254, s7, 61
	s_cselect_b64 s[6:7], -1, 0
	v_writelane_b32 v254, s6, 62
	s_cmp_eq_u32 s2, 4
	s_mov_b32 s21, -1
	v_writelane_b32 v254, s7, 63
	s_cselect_b64 s[6:7], -1, 0
	v_writelane_b32 v255, s6, 0
	s_cmp_eq_u32 s2, 3
	s_mov_b64 s[36:37], 0x80
	v_writelane_b32 v255, s7, 1
	s_cselect_b64 s[6:7], -1, 0
	v_writelane_b32 v255, s6, 2
	s_cmp_eq_u32 s2, 2
	s_mov_b64 s[82:83], 0x200
	v_writelane_b32 v255, s7, 3
	s_cselect_b64 s[6:7], -1, 0
	v_writelane_b32 v255, s6, 4
	s_cmp_eq_u32 s2, 1
	s_mov_b64 s[84:85], 0x400
	v_writelane_b32 v255, s7, 5
	s_cselect_b64 s[6:7], -1, 0
	v_writelane_b32 v255, s6, 6
	s_cmp_eq_u32 s2, 0
	s_nop 0
	v_writelane_b32 v255, s7, 7
	s_cselect_b64 s[6:7], -1, 0
	s_lshl_b32 s2, s2, 8
	s_add_u32 s2, s4, s2
	s_addc_u32 s3, s5, 0
	v_writelane_b32 v255, s6, 8
	s_add_u32 s4, s2, 0x1400
	s_addc_u32 s5, s3, 0
	v_writelane_b32 v255, s7, 9
	v_writelane_b32 v255, s4, 10
	s_add_u32 s2, s2, 0x2400
	s_addc_u32 s3, s3, 0
	v_writelane_b32 v255, s5, 11
	v_writelane_b32 v255, s2, 12
	s_nop 1
	v_writelane_b32 v255, s3, 13
	s_add_u32 s2, s0, 0x7400
	s_addc_u32 s3, s1, 0
	v_writelane_b32 v255, s2, 14
	s_add_u32 s0, s0, 0x7500
	s_addc_u32 s1, s1, 0
	v_writelane_b32 v255, s3, 15
	v_writelane_b32 v255, s0, 16
	s_mov_b32 s3, 0x66666667
	s_add_i32 s13, 0, 0x14800
	v_writelane_b32 v255, s1, 17
	s_movk_i32 s0, 0x3ff
	v_and_or_b32 v0, v0, s0, v212
	s_add_i32 s0, 0, 0x12900
	v_writelane_b32 v255, s0, 18
	s_add_i32 s0, 0, 0x1c840
	v_writelane_b32 v255, s0, 19
	s_add_i32 s0, 0, 0x1c804
	v_writelane_b32 v255, s0, 20
	s_add_i32 s0, 0, 0x1c808
	v_writelane_b32 v255, s0, 21
	s_add_i32 s0, 0, 0x1c80c
	v_writelane_b32 v255, s0, 22
	s_add_i32 s0, 0, 0x1c810
	v_writelane_b32 v255, s0, 23
	s_add_i32 s0, 0, 0x1c814
	v_writelane_b32 v255, s0, 24
	s_add_i32 s0, 0, 0x1c818
	v_writelane_b32 v255, s0, 25
	s_add_i32 s0, 0, 0x1c81c
	v_writelane_b32 v255, s0, 26
	v_cmp_eq_u32_e64 s[0:1], 0, v212
	s_add_i32 s16, 0, 0x14900
	s_nop 0
	v_writelane_b32 v255, s0, 27
	s_nop 1
	v_writelane_b32 v255, s1, 28
	v_cmp_eq_u32_e64 s[0:1], 0, v0
	s_nop 1
	v_writelane_b32 v255, s0, 29
	s_nop 1
	v_writelane_b32 v255, s1, 30
	v_writelane_b32 v255, s88, 31
	s_branch .LBB0_18
.LBB0_17:
	s_cmp_ge_i32 s27, s73
	s_mov_b32 s72, s27
	s_cbranch_scc1 .LBB0_797

; #define PG8_STAGE(bufoff, gbase, voff) do { _Pragma("unroll") for (int _i = 0; _i < 2; ++_i) \
;         __builtin_amdgcn_global_load_lds((const unsigned*)((const char*)(gbase) + (voff)[_i]), (PG8_LAS unsigned*)(lds + (bufoff) + ldsw + _i * 8192), 16, 0, 0); } while (0)
; #define PG8_LDA(dst, b, h) do { _Pragma("unroll") for (int m = 0; m < 4; ++m) _Pragma("unroll") for (int k = 0; k < 2; ++k) dst[m][k] = *(const PG8_LAS bf16x8*)(lds + PG8_SA(b, h) + aoff + m * 2048 + k * 1024); } while (0)
; #define PG8_LDB(dst, b, h) do { _Pragma("unroll") for (int n = 0; n < 2; ++n) _Pragma("unroll") for (int k = 0; k < 2; ++k) dst[n][k] = *(const PG8_LAS bf16x8*)(lds + PG8_SB(b, h) + boff + n * 2048 + k * 1024); } while (0)
; #define PG8_MMA(ai, bj, At, Bt) do { __builtin_amdgcn_s_setprio(1); _Pragma("unroll") for (int m = 0; m < 4; ++m) _Pragma("unroll") for (int n = 0; n < 2; ++n) _Pragma("unroll") for (int k = 0; k < 2; ++k) \
;         acc[ai][bj][m][n] = __builtin_amdgcn_mfma_f32_16x16x32_bf16(Bt[n][k], At[m][k], acc[ai][bj][m][n], 0, 0, 0); __builtin_amdgcn_s_setprio(0); } while (0)
; #define PG8_WAIT_V(n) asm volatile("s_waitcnt vmcnt(" #n ")" ::: "memory")
; #define PG8_WAIT_L(n) asm volatile("s_waitcnt lgkmcnt(" #n ")" ::: "memory")
; #define PG8_BAR __builtin_amdgcn_s_barrier()
; #define PG8_SCHED __builtin_amdgcn_sched_barrier(0)
; template <class Epi, class Sched, bool ALIGN_EPI = false, bool SP2 = false>
; __device__ __forceinline__ void gemm_phase(PG8_LAS unsigned char* lds, const Gemm g, const Sched& S, const Epi& E) {
;     ...
;             PG8_LDB(B0, 0, 0); PG8_LDB(B1, 0, 1); PG8_SCHED; PG8_LDA(At, 0, 0); PG8_STAGE(PG8_SA(1, 1), a1 + hstep, voffA);
;             PG8_WAIT_V(8); PG8_WAIT_L(0); PG8_BAR; PG8_MMA(0, 0, At, B0); PG8_MMA(0, 1, At, B1); PG8_BAR; PG8_SCHED;
;             PG8_LDA(At, 0, 1); PG8_STAGE(PG8_SB(0, 0), b2, voffB); PG8_STAGE(PG8_SB(0, 1), b2 + hstep, voffB); PG8_STAGE(PG8_SA(0, 0), a2, voffA);
;     ...
; #pragma unroll
;         for (int a = 0; a < 2; ++a)
; #pragma unroll
;             for (int b = 0; b < 2; ++b)
; #pragma unroll
;                 for (int m = 0; m < 4; ++m)
; #pragma unroll
;                     for (int n = 0; n < 2; ++n) acc[a][b][m][n] = (f32x4){0.f, 0.f, 0.f, 0.f};
.LBB0_641:
	s_ashr_i32 s45, s44, 31
	s_lshl_b64 s[46:47], s[44:45], 19
	s_add_u32 s46, s94, s46
	s_addc_u32 s47, s95, s47
	s_and_b64 s[48:49], s[40:41], exec
	s_cselect_b32 s26, s47, s53
	s_cselect_b32 s33, s46, s52
	s_ashr_i32 s43, s42, 31
	s_lshl_b64 s[48:49], s[42:43], 19
	s_add_u32 s48, s28, s48
	s_addc_u32 s49, s58, s49
	s_and_b64 s[56:57], s[40:41], exec
	s_cselect_b32 s43, s49, s55
	s_cselect_b32 s45, s48, s54
	s_add_u32 s52, s52, 0x40080
	s_addc_u32 s53, s53, 0
	s_add_u32 s51, s54, 0x100
	s_addc_u32 s70, s55, 0
	s_mov_b32 s71, -2
	s_add_u32 s54, s52, 0xfffc0080
	s_addc_u32 s55, s53, -1
	s_add_i32 s76, 0, 0x10000
	s_cmp_eq_u32 s71, 12
	s_cselect_b32 s57, s26, s55
	s_cselect_b32 s56, s33, s54
	s_cselect_b32 s55, s43, s70
	s_cselect_b32 s54, s45, s51
	s_add_i32 s88, 0, 0x14000
	v_add_u32_e32 v156, s76, v146
	v_add_u32_e32 v172, s88, v146
	ds_read_b128 v[140:143], v156
	ds_read_b128 v[148:151], v156 offset:1024
	ds_read_b128 v[152:155], v156 offset:2048
	ds_read_b128 v[156:159], v156 offset:3072
	ds_read_b128 v[160:163], v172
	ds_read_b128 v[164:167], v172 offset:1024
	ds_read_b128 v[168:171], v172 offset:2048
	ds_read_b128 v[172:175], v172 offset:3072
	v_lshl_add_u64 v[238:239], s[52:53], 0, v[136:137]
	s_add_i32 m0, s60, 0xc000
	ds_read_b128 v[176:179], v147
	ds_read_b128 v[180:183], v147 offset:1024
	ds_read_b128 v[184:187], v147 offset:2048
	ds_read_b128 v[188:191], v147 offset:3072
	ds_read_b128 v[192:195], v147 offset:4096
	ds_read_b128 v[208:211], v147 offset:5120
	ds_read_b128 v[230:233], v147 offset:6144
	ds_read_b128 v[234:237], v147 offset:7168
	global_load_lds_dwordx4 v[238:239], off
	v_lshl_add_u64 v[238:239], s[52:53], 0, v[138:139]
	s_add_i32 m0, s60, 0xe000
	s_nop 0
	global_load_lds_dwordx4 v[238:239], off
	s_waitcnt vmcnt(8)
	s_waitcnt lgkmcnt(0)
	s_barrier
	s_setprio 1
	s_waitcnt lgkmcnt(0)
	v_mfma_f32_16x16x32_bf16 v[128:131], v[140:143], v[176:179], 0
	v_mfma_f32_16x16x32_bf16 v[124:127], v[152:155], v[176:179], 0
	v_mfma_f32_16x16x32_bf16 v[112:115], v[140:143], v[184:187], 0
	v_mfma_f32_16x16x32_bf16 v[108:111], v[152:155], v[184:187], 0
	v_mfma_f32_16x16x32_bf16 v[96:99], v[140:143], v[192:195], 0
	v_mfma_f32_16x16x32_bf16 v[92:95], v[152:155], v[192:195], 0
	v_mfma_f32_16x16x32_bf16 v[80:83], v[140:143], v[230:233], 0
	v_mfma_f32_16x16x32_bf16 v[76:79], v[152:155], v[230:233], 0
	v_mfma_f32_16x16x32_bf16 v[128:131], v[148:151], v[180:183], v[128:131]
	v_mfma_f32_16x16x32_bf16 v[124:127], v[156:159], v[180:183], v[124:127]
	v_mfma_f32_16x16x32_bf16 v[112:115], v[148:151], v[188:191], v[112:115]
	v_mfma_f32_16x16x32_bf16 v[108:111], v[156:159], v[188:191], v[108:111]
	v_mfma_f32_16x16x32_bf16 v[96:99], v[148:151], v[208:211], v[96:99]
	v_mfma_f32_16x16x32_bf16 v[92:95], v[156:159], v[208:211], v[92:95]
	v_mfma_f32_16x16x32_bf16 v[80:83], v[148:151], v[234:237], v[80:83]
	v_mfma_f32_16x16x32_bf16 v[76:79], v[156:159], v[234:237], v[76:79]
	s_setprio 0
	s_setprio 1
	v_mfma_f32_16x16x32_bf16 v[120:123], v[160:163], v[176:179], 0
	v_mfma_f32_16x16x32_bf16 v[116:119], v[168:171], v[176:179], 0
	v_mfma_f32_16x16x32_bf16 v[104:107], v[160:163], v[184:187], 0
	v_mfma_f32_16x16x32_bf16 v[100:103], v[168:171], v[184:187], 0
	v_mfma_f32_16x16x32_bf16 v[88:91], v[160:163], v[192:195], 0
	v_mfma_f32_16x16x32_bf16 v[84:87], v[168:171], v[192:195], 0
	v_mfma_f32_16x16x32_bf16 v[72:75], v[160:163], v[230:233], 0
	v_mfma_f32_16x16x32_bf16 v[68:71], v[168:171], v[230:233], 0
	v_mfma_f32_16x16x32_bf16 v[120:123], v[164:167], v[180:183], v[120:123]
	v_mfma_f32_16x16x32_bf16 v[116:119], v[172:175], v[180:183], v[116:119]
	v_mfma_f32_16x16x32_bf16 v[104:107], v[164:167], v[188:191], v[104:107]
	v_mfma_f32_16x16x32_bf16 v[100:103], v[172:175], v[188:191], v[100:103]
	v_mfma_f32_16x16x32_bf16 v[88:91], v[164:167], v[208:211], v[88:91]
	v_mfma_f32_16x16x32_bf16 v[84:87], v[172:175], v[208:211], v[84:87]
	v_mfma_f32_16x16x32_bf16 v[72:75], v[164:167], v[234:237], v[72:75]
	v_mfma_f32_16x16x32_bf16 v[68:71], v[172:175], v[234:237], v[68:71]
	s_setprio 0
	s_barrier
	s_add_i32 s76, s76, s59
	v_lshl_add_u64 v[238:239], s[54:55], 0, v[2:3]
	s_mov_b32 m0, s76
	ds_read_b128 v[176:179], v147 offset:16384
	ds_read_b128 v[180:183], v147 offset:17408
	ds_read_b128 v[184:187], v147 offset:18432
	ds_read_b128 v[188:191], v147 offset:19456
	ds_read_b128 v[192:195], v147 offset:20480
	ds_read_b128 v[208:211], v147 offset:21504
	ds_read_b128 v[230:233], v147 offset:22528
	ds_read_b128 v[234:237], v147 offset:23552
	global_load_lds_dwordx4 v[238:239], off
	s_add_i32 m0, s76, 0x2000
	s_add_u32 s76, s54, 0x40000
	v_lshl_add_u64 v[240:241], s[54:55], 0, v[134:135]
	s_addc_u32 s77, s55, 0
	s_add_i32 s88, s88, s59
	global_load_lds_dwordx4 v[240:241], off
	v_lshl_add_u64 v[242:243], s[76:77], 0, v[2:3]
	s_mov_b32 m0, s88
	v_lshl_add_u64 v[244:245], s[56:57], 0, v[132:133]
	global_load_lds_dwordx4 v[242:243], off
	v_lshl_add_u64 v[242:243], s[76:77], 0, v[134:135]
	s_add_i32 m0, s88, 0x2000
	s_nop 0
	global_load_lds_dwordx4 v[242:243], off
	v_lshl_add_u64 v[242:243], s[56:57], 0, v[0:1]
	s_mov_b32 m0, s60
	s_nop 0
	global_load_lds_dwordx4 v[242:243], off
	s_mov_b32 m0, s61
	s_nop 0
	global_load_lds_dwordx4 v[244:245], off
	s_waitcnt vmcnt(8)
	s_waitcnt lgkmcnt(0)
	s_barrier
; #define PG8_STAGE(bufoff, gbase, voff) do { _Pragma("unroll") for (int _i = 0; _i < 2; ++_i) \
;         __builtin_amdgcn_global_load_lds((const unsigned*)((const char*)(gbase) + (voff)[_i]), (PG8_LAS unsigned*)(lds + (bufoff) + ldsw + _i * 8192), 16, 0, 0); } while (0)
; #define PG8_LDA(dst, b, h) do { _Pragma("unroll") for (int m = 0; m < 4; ++m) _Pragma("unroll") for (int k = 0; k < 2; ++k) dst[m][k] = *(const PG8_LAS bf16x8*)(lds + PG8_SA(b, h) + aoff + m * 2048 + k * 1024); } while (0)
; #define PG8_LDB(dst, b, h) do { _Pragma("unroll") for (int n = 0; n < 2; ++n) _Pragma("unroll") for (int k = 0; k < 2; ++k) dst[n][k] = *(const PG8_LAS bf16x8*)(lds + PG8_SB(b, h) + boff + n * 2048 + k * 1024); } while (0)
; #define PG8_MMA(ai, bj, At, Bt) do { __builtin_amdgcn_s_setprio(1); _Pragma("unroll") for (int m = 0; m < 4; ++m) _Pragma("unroll") for (int n = 0; n < 2; ++n) _Pragma("unroll") for (int k = 0; k < 2; ++k) \
;         acc[ai][bj][m][n] = __builtin_amdgcn_mfma_f32_16x16x32_bf16(Bt[n][k], At[m][k], acc[ai][bj][m][n], 0, 0, 0); __builtin_amdgcn_s_setprio(0); } while (0)
; #define PG8_WAIT_V(n) asm volatile("s_waitcnt vmcnt(" #n ")" ::: "memory")
; #define PG8_WAIT_L(n) asm volatile("s_waitcnt lgkmcnt(" #n ")" ::: "memory")
; #define PG8_BAR __builtin_amdgcn_s_barrier()
; #define PG8_SCHED __builtin_amdgcn_sched_barrier(0)
; template <class Epi, class Sched, bool ALIGN_EPI = false, bool SP2 = false>
; __device__ __forceinline__ void gemm_phase(PG8_LAS unsigned char* lds, const Gemm g, const Sched& S, const Epi& E) {
;     ...
;             PG8_WAIT_V(8); PG8_WAIT_L(0); PG8_BAR; PG8_MMA(1, 0, At, B0); PG8_MMA(1, 1, At, B1); PG8_BAR; PG8_SCHED;
;             PG8_LDB(B0, 1, 0); PG8_LDB(B1, 1, 1); PG8_SCHED; PG8_LDA(At, 1, 0); PG8_STAGE(PG8_SA(0, 1), a2 + hstep, voffA);
;             PG8_WAIT_V(8); PG8_WAIT_L(0); PG8_BAR; PG8_MMA(0, 0, At, B0); PG8_MMA(0, 1, At, B1); PG8_BAR; PG8_SCHED;
	s_setprio 1
	s_waitcnt lgkmcnt(0)
	v_mfma_f32_16x16x32_bf16 v[64:67], v[140:143], v[176:179], 0
	v_mfma_f32_16x16x32_bf16 v[60:63], v[152:155], v[176:179], 0
	v_mfma_f32_16x16x32_bf16 v[48:51], v[140:143], v[184:187], 0
	v_mfma_f32_16x16x32_bf16 v[44:47], v[152:155], v[184:187], 0
	v_mfma_f32_16x16x32_bf16 v[32:35], v[140:143], v[192:195], 0
	v_mfma_f32_16x16x32_bf16 v[28:31], v[152:155], v[192:195], 0
	v_mfma_f32_16x16x32_bf16 v[16:19], v[140:143], v[230:233], 0
	v_mfma_f32_16x16x32_bf16 v[12:15], v[152:155], v[230:233], 0
	v_mfma_f32_16x16x32_bf16 v[64:67], v[148:151], v[180:183], v[64:67]
	v_mfma_f32_16x16x32_bf16 v[60:63], v[156:159], v[180:183], v[60:63]
	v_mfma_f32_16x16x32_bf16 v[48:51], v[148:151], v[188:191], v[48:51]
	v_mfma_f32_16x16x32_bf16 v[44:47], v[156:159], v[188:191], v[44:47]
	v_mfma_f32_16x16x32_bf16 v[32:35], v[148:151], v[208:211], v[32:35]
	v_mfma_f32_16x16x32_bf16 v[28:31], v[156:159], v[208:211], v[28:31]
	v_mfma_f32_16x16x32_bf16 v[16:19], v[148:151], v[234:237], v[16:19]
	v_mfma_f32_16x16x32_bf16 v[12:15], v[156:159], v[234:237], v[12:15]
	s_setprio 0
	s_setprio 1
	v_mfma_f32_16x16x32_bf16 v[56:59], v[160:163], v[176:179], 0
	v_mfma_f32_16x16x32_bf16 v[52:55], v[168:171], v[176:179], 0
	v_mfma_f32_16x16x32_bf16 v[40:43], v[160:163], v[184:187], 0
	v_mfma_f32_16x16x32_bf16 v[36:39], v[168:171], v[184:187], 0
	v_mfma_f32_16x16x32_bf16 v[24:27], v[160:163], v[192:195], 0
	v_mfma_f32_16x16x32_bf16 v[20:23], v[168:171], v[192:195], 0
	v_mfma_f32_16x16x32_bf16 v[8:11], v[160:163], v[230:233], 0
	v_mfma_f32_16x16x32_bf16 v[4:7], v[168:171], v[230:233], 0
	v_mfma_f32_16x16x32_bf16 v[56:59], v[164:167], v[180:183], v[56:59]
	v_mfma_f32_16x16x32_bf16 v[52:55], v[172:175], v[180:183], v[52:55]
	v_mfma_f32_16x16x32_bf16 v[40:43], v[164:167], v[188:191], v[40:43]
	v_mfma_f32_16x16x32_bf16 v[36:39], v[172:175], v[188:191], v[36:39]
	v_mfma_f32_16x16x32_bf16 v[24:27], v[164:167], v[208:211], v[24:27]
	v_mfma_f32_16x16x32_bf16 v[20:23], v[172:175], v[208:211], v[20:23]
	v_mfma_f32_16x16x32_bf16 v[8:11], v[164:167], v[234:237], v[8:11]
	v_mfma_f32_16x16x32_bf16 v[4:7], v[172:175], v[234:237], v[4:7]
	s_setprio 0
	s_barrier
	s_add_i32 s76, 0, 0x18000
	s_add_i32 s77, 0, 0x1c000
	v_add_u32_e32 v156, s76, v146
	v_add_u32_e32 v172, s77, v146
	ds_read_b128 v[140:143], v156
	ds_read_b128 v[148:151], v156 offset:1024
	ds_read_b128 v[152:155], v156 offset:2048
	ds_read_b128 v[156:159], v156 offset:3072
	ds_read_b128 v[160:163], v172
	ds_read_b128 v[164:167], v172 offset:1024
	ds_read_b128 v[168:171], v172 offset:2048
	ds_read_b128 v[172:175], v172 offset:3072
	s_add_u32 s56, s56, 0x40000
	s_addc_u32 s57, s57, 0
	s_mov_b32 m0, s62
	v_lshl_add_u64 v[246:247], s[56:57], 0, v[0:1]
	ds_read_b128 v[176:179], v147 offset:32768
	ds_read_b128 v[180:183], v147 offset:33792
	ds_read_b128 v[184:187], v147 offset:34816
	ds_read_b128 v[188:191], v147 offset:35840
	ds_read_b128 v[192:195], v147 offset:36864
	ds_read_b128 v[208:211], v147 offset:37888
	ds_read_b128 v[230:233], v147 offset:38912
	ds_read_b128 v[234:237], v147 offset:39936
	global_load_lds_dwordx4 v[246:247], off
	v_lshl_add_u64 v[246:247], s[56:57], 0, v[132:133]
	s_mov_b32 m0, s63
	s_nop 0
	global_load_lds_dwordx4 v[246:247], off
	s_waitcnt vmcnt(8)
	s_waitcnt lgkmcnt(0)
	s_barrier
	s_setprio 1
	s_waitcnt lgkmcnt(0)
	v_mfma_f32_16x16x32_bf16 v[128:131], v[140:143], v[176:179], v[128:131]
	v_mfma_f32_16x16x32_bf16 v[124:127], v[152:155], v[176:179], v[124:127]
	v_mfma_f32_16x16x32_bf16 v[112:115], v[140:143], v[184:187], v[112:115]
	v_mfma_f32_16x16x32_bf16 v[108:111], v[152:155], v[184:187], v[108:111]
	v_mfma_f32_16x16x32_bf16 v[96:99], v[140:143], v[192:195], v[96:99]
	v_mfma_f32_16x16x32_bf16 v[92:95], v[152:155], v[192:195], v[92:95]
	v_mfma_f32_16x16x32_bf16 v[80:83], v[140:143], v[230:233], v[80:83]
	v_mfma_f32_16x16x32_bf16 v[76:79], v[152:155], v[230:233], v[76:79]
	v_mfma_f32_16x16x32_bf16 v[128:131], v[148:151], v[180:183], v[128:131]
	v_mfma_f32_16x16x32_bf16 v[124:127], v[156:159], v[180:183], v[124:127]
	v_mfma_f32_16x16x32_bf16 v[112:115], v[148:151], v[188:191], v[112:115]
	v_mfma_f32_16x16x32_bf16 v[108:111], v[156:159], v[188:191], v[108:111]
	v_mfma_f32_16x16x32_bf16 v[96:99], v[148:151], v[208:211], v[96:99]
	v_mfma_f32_16x16x32_bf16 v[92:95], v[156:159], v[208:211], v[92:95]
	v_mfma_f32_16x16x32_bf16 v[80:83], v[148:151], v[234:237], v[80:83]
	v_mfma_f32_16x16x32_bf16 v[76:79], v[156:159], v[234:237], v[76:79]
	s_setprio 0
	s_setprio 1
	v_mfma_f32_16x16x32_bf16 v[120:123], v[160:163], v[176:179], v[120:123]
	v_mfma_f32_16x16x32_bf16 v[116:119], v[168:171], v[176:179], v[116:119]
	v_mfma_f32_16x16x32_bf16 v[104:107], v[160:163], v[184:187], v[104:107]
	v_mfma_f32_16x16x32_bf16 v[100:103], v[168:171], v[184:187], v[100:103]
	v_mfma_f32_16x16x32_bf16 v[88:91], v[160:163], v[192:195], v[88:91]
	v_mfma_f32_16x16x32_bf16 v[84:87], v[168:171], v[192:195], v[84:87]
	v_mfma_f32_16x16x32_bf16 v[72:75], v[160:163], v[230:233], v[72:75]
	v_mfma_f32_16x16x32_bf16 v[68:71], v[168:171], v[230:233], v[68:71]
	v_mfma_f32_16x16x32_bf16 v[120:123], v[164:167], v[180:183], v[120:123]
	v_mfma_f32_16x16x32_bf16 v[116:119], v[172:175], v[180:183], v[116:119]
	v_mfma_f32_16x16x32_bf16 v[104:107], v[164:167], v[188:191], v[104:107]
	v_mfma_f32_16x16x32_bf16 v[100:103], v[172:175], v[188:191], v[100:103]
	v_mfma_f32_16x16x32_bf16 v[88:91], v[164:167], v[208:211], v[88:91]
	v_mfma_f32_16x16x32_bf16 v[84:87], v[172:175], v[208:211], v[84:87]
	v_mfma_f32_16x16x32_bf16 v[72:75], v[164:167], v[234:237], v[72:75]
	v_mfma_f32_16x16x32_bf16 v[68:71], v[172:175], v[234:237], v[68:71]
	s_setprio 0
	s_barrier
; #define PG8_STAGE(bufoff, gbase, voff) do { _Pragma("unroll") for (int _i = 0; _i < 2; ++_i) \
;         __builtin_amdgcn_global_load_lds((const unsigned*)((const char*)(gbase) + (voff)[_i]), (PG8_LAS unsigned*)(lds + (bufoff) + ldsw + _i * 8192), 16, 0, 0); } while (0)
; #define PG8_LDA(dst, b, h) do { _Pragma("unroll") for (int m = 0; m < 4; ++m) _Pragma("unroll") for (int k = 0; k < 2; ++k) dst[m][k] = *(const PG8_LAS bf16x8*)(lds + PG8_SA(b, h) + aoff + m * 2048 + k * 1024); } while (0)
; #define PG8_MMA(ai, bj, At, Bt) do { __builtin_amdgcn_s_setprio(1); _Pragma("unroll") for (int m = 0; m < 4; ++m) _Pragma("unroll") for (int n = 0; n < 2; ++n) _Pragma("unroll") for (int k = 0; k < 2; ++k) \
;         acc[ai][bj][m][n] = __builtin_amdgcn_mfma_f32_16x16x32_bf16(Bt[n][k], At[m][k], acc[ai][bj][m][n], 0, 0, 0); __builtin_amdgcn_s_setprio(0); } while (0)
; #define PG8_WAIT_V(n) asm volatile("s_waitcnt vmcnt(" #n ")" ::: "memory")
; #define PG8_WAIT_L(n) asm volatile("s_waitcnt lgkmcnt(" #n ")" ::: "memory")
; #define PG8_BAR __builtin_amdgcn_s_barrier()
; #define PG8_SCHED __builtin_amdgcn_sched_barrier(0)
; template <class Epi, class Sched, bool ALIGN_EPI = false, bool SP2 = false>
; __device__ __forceinline__ void gemm_phase(PG8_LAS unsigned char* lds, const Gemm g, const Sched& S, const Epi& E) {
;     ...
;         for (int t = 0; t < nt; t += 2) {
;             const bool last = (t == nt - 2);
;             const char* a1 = cA + (size_t)(t + 1) * kstep;
;             const char* a2 = last ? nA : cA + (size_t)(t + 2) * kstep; const char* b2 = last ? nB : cB + (size_t)(t + 2) * kstep;
;             const char* a3 = a2 + kstep; const char* b3 = b2 + kstep;
;     ...
;             PG8_LDA(At, 1, 1); PG8_STAGE(PG8_SB(1, 0), b3, voffB); PG8_STAGE(PG8_SB(1, 1), b3 + hstep, voffB); PG8_STAGE(PG8_SA(1, 0), a3, voffA);
;             PG8_WAIT_V(8); PG8_WAIT_L(0); PG8_BAR; PG8_MMA(1, 0, At, B0); PG8_MMA(1, 1, At, B1); PG8_BAR; PG8_SCHED;
	s_add_i32 s56, s76, s59
	v_lshl_add_u64 v[238:239], v[238:239], 0, s[36:37]
	s_mov_b32 m0, s56
	ds_read_b128 v[176:179], v147 offset:49152
	ds_read_b128 v[180:183], v147 offset:50176
	ds_read_b128 v[184:187], v147 offset:51200
	ds_read_b128 v[188:191], v147 offset:52224
	ds_read_b128 v[192:195], v147 offset:53248
	ds_read_b128 v[208:211], v147 offset:54272
	ds_read_b128 v[230:233], v147 offset:55296
	ds_read_b128 v[234:237], v147 offset:56320
	global_load_lds_dwordx4 v[238:239], off
	s_add_i32 m0, s56, 0x2000
	s_add_u32 s54, s54, 0x40080
	v_lshl_add_u64 v[238:239], v[240:241], 0, s[36:37]
	s_addc_u32 s55, s55, 0
	s_add_i32 s56, s77, s59
	global_load_lds_dwordx4 v[238:239], off
	v_lshl_add_u64 v[238:239], s[54:55], 0, v[2:3]
	s_mov_b32 m0, s56
	s_nop 0
	global_load_lds_dwordx4 v[238:239], off
	v_lshl_add_u64 v[238:239], s[54:55], 0, v[134:135]
	s_add_i32 m0, s56, 0x2000
	s_nop 0
	global_load_lds_dwordx4 v[238:239], off
	v_lshl_add_u64 v[238:239], v[242:243], 0, s[36:37]
	s_mov_b32 m0, s66
	s_nop 0
	global_load_lds_dwordx4 v[238:239], off
	v_lshl_add_u64 v[238:239], v[244:245], 0, s[36:37]
	s_mov_b32 m0, s67
	s_nop 0
	global_load_lds_dwordx4 v[238:239], off
	s_waitcnt vmcnt(8)
	s_waitcnt lgkmcnt(0)
	s_barrier
	s_setprio 1
	s_waitcnt lgkmcnt(0)
	v_mfma_f32_16x16x32_bf16 v[64:67], v[140:143], v[176:179], v[64:67]
	v_mfma_f32_16x16x32_bf16 v[60:63], v[152:155], v[176:179], v[60:63]
	v_mfma_f32_16x16x32_bf16 v[48:51], v[140:143], v[184:187], v[48:51]
	v_mfma_f32_16x16x32_bf16 v[44:47], v[152:155], v[184:187], v[44:47]
	v_mfma_f32_16x16x32_bf16 v[32:35], v[140:143], v[192:195], v[32:35]
	v_mfma_f32_16x16x32_bf16 v[28:31], v[152:155], v[192:195], v[28:31]
	v_mfma_f32_16x16x32_bf16 v[16:19], v[140:143], v[230:233], v[16:19]
	v_mfma_f32_16x16x32_bf16 v[12:15], v[152:155], v[230:233], v[12:15]
	v_mfma_f32_16x16x32_bf16 v[64:67], v[148:151], v[180:183], v[64:67]
	v_mfma_f32_16x16x32_bf16 v[60:63], v[156:159], v[180:183], v[60:63]
	v_mfma_f32_16x16x32_bf16 v[48:51], v[148:151], v[188:191], v[48:51]
	v_mfma_f32_16x16x32_bf16 v[44:47], v[156:159], v[188:191], v[44:47]
	v_mfma_f32_16x16x32_bf16 v[32:35], v[148:151], v[208:211], v[32:35]
	v_mfma_f32_16x16x32_bf16 v[28:31], v[156:159], v[208:211], v[28:31]
	v_mfma_f32_16x16x32_bf16 v[16:19], v[148:151], v[234:237], v[16:19]
	v_mfma_f32_16x16x32_bf16 v[12:15], v[156:159], v[234:237], v[12:15]
	s_setprio 0
	s_setprio 1
	v_mfma_f32_16x16x32_bf16 v[56:59], v[160:163], v[176:179], v[56:59]
	v_mfma_f32_16x16x32_bf16 v[52:55], v[168:171], v[176:179], v[52:55]
	v_mfma_f32_16x16x32_bf16 v[40:43], v[160:163], v[184:187], v[40:43]
	v_mfma_f32_16x16x32_bf16 v[36:39], v[168:171], v[184:187], v[36:39]
	v_mfma_f32_16x16x32_bf16 v[24:27], v[160:163], v[192:195], v[24:27]
	v_mfma_f32_16x16x32_bf16 v[20:23], v[168:171], v[192:195], v[20:23]
	v_mfma_f32_16x16x32_bf16 v[8:11], v[160:163], v[230:233], v[8:11]
	v_mfma_f32_16x16x32_bf16 v[4:7], v[168:171], v[230:233], v[4:7]
	v_mfma_f32_16x16x32_bf16 v[56:59], v[164:167], v[180:183], v[56:59]
	v_mfma_f32_16x16x32_bf16 v[52:55], v[172:175], v[180:183], v[52:55]
	v_mfma_f32_16x16x32_bf16 v[40:43], v[164:167], v[188:191], v[40:43]
	v_mfma_f32_16x16x32_bf16 v[36:39], v[172:175], v[188:191], v[36:39]
	v_mfma_f32_16x16x32_bf16 v[24:27], v[164:167], v[208:211], v[24:27]
	v_mfma_f32_16x16x32_bf16 v[20:23], v[172:175], v[208:211], v[20:23]
	v_mfma_f32_16x16x32_bf16 v[8:11], v[164:167], v[234:237], v[8:11]
	v_mfma_f32_16x16x32_bf16 v[4:7], v[172:175], v[234:237], v[4:7]
	s_setprio 0
	s_barrier
	s_add_i32 s71, s71, 2
	s_add_u32 s52, s52, 0x100
	s_addc_u32 s53, s53, 0
	s_add_u32 s51, s51, 0x100
	s_addc_u32 s70, s70, 0

; __device__ __forceinline__ void xcd_barrier(const XcdBarrier& b) {
;     asm volatile("s_waitcnt vmcnt(0)" ::: "memory");
;     __syncthreads();
;     if (threadIdx.x == 0) {
;         unsigned* bar = b.bar;
;         __builtin_amdgcn_s_waitcnt(0);
;         unsigned nloc = b.st[0], nx = b.st[1];
;         if (nloc == 0u) { xcd_barrier_complete(bar, b.x, nloc, nx); b.st[0] = nloc; b.st[1] = nx; }
; __global__ void __launch_bounds__(NWAVES * 64, 2) mk_fwd(Args args) {
;     ...
;         const bool again = (((PROBE_MASK >> p) & 1u) != 0u) && rep == 0;
;         if (did && (p + 1 < args.ph_hi || again)) {
;             if (p == 0 && !again) { __syncthreads(); cg::this_grid().sync(); } else xcd_barrier(bar);
.LBB0_735:
	s_and_b64 vcc, exec, s[4:5]
	s_cbranch_vccz .LBB0_17
	s_add_i32 s27, s72, 1
	s_cmp_ge_i32 s27, s73
	s_cbranch_scc1 .LBB0_17
	s_waitcnt vmcnt(0)
	s_waitcnt vmcnt(0) lgkmcnt(0)
	s_barrier
	s_mov_b64 s[0:1], exec
	v_readlane_b32 s4, v255, 27
	v_readlane_b32 s5, v255, 28
	s_and_b64 s[4:5], s[0:1], s[4:5]
	v_readlane_b32 s19, v254, 2
	s_mov_b64 exec, s[4:5]
	s_cbranch_execz .LBB0_787
	v_mov_b32_e32 v0, s19
	s_waitcnt vmcnt(0) expcnt(0) lgkmcnt(0)
	ds_read_b32 v2, v0
	ds_read_b32 v0, v0 offset:4
	s_waitcnt lgkmcnt(1)
	v_cmp_ne_u32_e32 vcc, 0, v2
	s_cbranch_vccnz .LBB0_755
	v_readlane_b32 s6, v254, 3
	v_readlane_b32 s7, v254, 4
	s_load_dwordx2 s[4:5], s[6:7], 0x4
	v_readlane_b32 s2, v255, 32
	s_mov_b32 s14, 1
	s_waitcnt lgkmcnt(0)
	s_mul_i32 s2, s4, s2
	s_mul_i32 s2, s2, s5
	s_branch .LBB0_742

; __device__ __forceinline__ unsigned xb_ld(unsigned* p)              { return __hip_atomic_load(p, __ATOMIC_RELAXED, __HIP_MEMORY_SCOPE_AGENT); }
; __device__ __forceinline__ void xcd_barrier_complete(unsigned* bar, unsigned x, unsigned& nloc, unsigned& nx) {
;     ...
;     for (;;) {
;         sum = 0u; cnt = 0u; mine = 0u;
; #pragma unroll
;         for (unsigned j = 0; j < 16; ++j) { const unsigned c = xb_ld(&bar[XB_XCNT(j)]); sum += c; cnt += (c > 0u) ? 1u : 0u; mine = (j == x) ? c : mine; }
;         if (sum == G) break;
;         __builtin_amdgcn_s_sleep(1);
;         if ((++sp & 255u) == 0u) { if (xb_ld(&bar[XB_TMO])) break; if (sp > XB_SPIN_CAP) { atomicAdd(&bar[XB_TMO], 1u); break; } }
;     }
;     nloc = mine > 0u ? mine : 1u; nx = cnt > 0u ? cnt : 1u;
.LBB0_748:
	s_cmp_lt_u32 s14, 0x40001
	s_mov_b64 s[4:5], 0
	s_cselect_b64 s[8:9], -1, 0
	s_and_b64 vcc, exec, s[8:9]
	s_cbranch_vccz .LBB0_741
	s_branch .LBB0_747
.LBB0_750:
	s_andn2_b64 vcc, exec, s[4:5]
	s_cbranch_vccz .LBB0_754
	s_mov_b64 s[6:7], exec
	v_mbcnt_lo_u32_b32 v17, s6, 0
	v_mbcnt_hi_u32_b32 v17, s7, v17
	v_cmp_eq_u32_e32 vcc, 0, v17
	s_and_saveexec_b64 s[4:5], vcc
	s_cbranch_execz .LBB0_753
	s_bcnt1_i32_b64 s2, s[6:7]
	v_readlane_b32 s6, v254, 8
	v_mov_b32_e32 v17, s2
	v_readlane_b32 s7, v254, 9
	s_nop 4
	global_atomic_add v3, v17, s[6:7]

; __device__ __forceinline__ void xcd_barrier(const XcdBarrier& b) {
;     ...
;     __syncthreads();
; }
; __global__ void __launch_bounds__(NWAVES * 64, 2) mk_fwd(Args args) {
;     ...
;             if (p == 0 && !again) { __syncthreads(); cg::this_grid().sync(); } else xcd_barrier(bar);
.LBB0_787:
	s_or_b64 exec, exec, s[0:1]
	s_waitcnt lgkmcnt(0)
	s_barrier
	s_branch .LBB0_17
.LBB0_797:
	s_endpgm
